# v017 + attention: per-lane LDS-DMA source offsets precomputed once per workgroup in free LDS, read back per tile instead of recomputed
# speedup vs baseline: 1.0096x; 1.0042x over previous
.LBB0_2728:
	s_add_u32 s2, s4, s0
	s_addc_u32 s3, s5, s1
	global_load_dwordx4 v[4:7], v1, s[2:3]
	global_load_dwordx4 v[8:11], v1, s[2:3] offset:16
	s_add_u32 s2, s6, s0
	s_addc_u32 s3, s7, s1
	global_load_dwordx4 v[12:15], v1, s[2:3]
	global_load_dwordx4 v[16:19], v1, s[2:3] offset:16
	s_add_u32 s2, s8, s0
	s_addc_u32 s3, s9, s1
	global_load_dwordx4 v[20:23], v1, s[2:3]
	global_load_dwordx4 v[24:27], v1, s[2:3] offset:16
	s_add_u32 s2, s10, s0
	s_addc_u32 s3, s11, s1
	global_load_dwordx4 v[28:31], v1, s[2:3]
	global_load_dwordx4 v[32:35], v1, s[2:3] offset:16
	s_add_u32 s0, s0, 32
	s_addc_u32 s1, s1, 0
	s_cmpk_lg_i32 s0, 0x200
	s_waitcnt vmcnt(7)
	v_mov_b32_e32 v37, v4
	v_mov_b32_e32 v39, v6
	s_waitcnt vmcnt(6)
	v_mov_b32_e32 v41, v8
	s_waitcnt vmcnt(5)
	v_mov_b32_e32 v45, v12
	v_mov_b32_e32 v47, v14
	s_waitcnt vmcnt(4)
	v_mov_b32_e32 v49, v16
	s_waitcnt vmcnt(3)
	v_mov_b32_e32 v36, v20
	v_mov_b32_e32 v4, v21
	v_mov_b32_e32 v38, v22
	s_waitcnt vmcnt(1)
	v_mov_b32_e32 v44, v28
	v_mov_b32_e32 v12, v29
	v_pk_fma_f32 v[2:3], v[36:37], v[44:45], v[2:3]
	v_mov_b32_e32 v46, v30
	v_pk_fma_f32 v[2:3], v[4:5], v[12:13], v[2:3]
	v_mov_b32_e32 v6, v23
	v_mov_b32_e32 v14, v31
	v_pk_fma_f32 v[2:3], v[38:39], v[46:47], v[2:3]
	v_mov_b32_e32 v40, v24
	s_waitcnt vmcnt(0)
	v_mov_b32_e32 v48, v32
	v_pk_fma_f32 v[2:3], v[6:7], v[14:15], v[2:3]
	v_mov_b32_e32 v8, v25
	v_mov_b32_e32 v16, v33
	v_pk_fma_f32 v[2:3], v[40:41], v[48:49], v[2:3]
	v_mov_b32_e32 v43, v10
	v_mov_b32_e32 v51, v18
	v_mov_b32_e32 v42, v26
	v_mov_b32_e32 v50, v34
	v_pk_fma_f32 v[2:3], v[8:9], v[16:17], v[2:3]
	v_mov_b32_e32 v10, v27
	v_mov_b32_e32 v18, v35
	v_pk_fma_f32 v[2:3], v[42:43], v[50:51], v[2:3]
	s_nop 0
	v_pk_fma_f32 v[2:3], v[10:11], v[18:19], v[2:3]
	s_cbranch_scc1 .LBB0_2728
	s_add_u32 s0, s92, 0x30d00000
	v_writelane_b32 v255, s0, 20
	s_addc_u32 s0, s93, 0
	v_writelane_b32 v255, s0, 6
	s_getreg_b32 s0, hwreg(HW_REG_XCC_ID, 0, 4)
	s_and_b32 s0, s0, 15
	s_add_u32 s2, s92, 0x34e00000
	s_addc_u32 s3, s93, 0
	v_writelane_b32 v254, s2, 3
	v_writelane_b32 v255, s0, 10
	s_add_u32 s55, s92, 0x38f00000
	v_writelane_b32 v254, s3, 4
	v_writelane_b32 v255, s92, 21
	v_readlane_b32 s7, v254, 0
	s_addc_u32 s95, s93, 0
	s_lshr_b32 s2, s7, 7
	s_bfe_u32 s3, s7, 0x10006
	s_lshl_b32 s46, s2, 5
	s_cmpk_lt_u32 s7, 0x200
	v_readlane_b32 s8, v254, 28
	s_cselect_b64 s[56:57], -1, 0
	s_lshl_b32 s5, s8, 5
	v_writelane_b32 v255, s93, 22
	s_and_b32 s5, s5, 0x7fffff80
	v_mul_f32_e32 v1, 0x3fb8aa3b, v3
	v_mul_f32_e32 v2, 0x3fb8aa3b, v2
	s_lshl_b32 s4, s8, 2
	v_writelane_b32 v255, s5, 11
	s_lshl_b32 s5, s8, 4
	v_exp_f32_e32 v1, v1
	v_exp_f32_e32 v2, v2
	s_and_b32 s80, s5, 48
	s_or_b32 s5, s4, 1
	s_lshl_b32 s81, s8, 12
	s_lshl_b32 s6, s5, 2
	s_lshl_b32 s83, s5, 10
	s_or_b32 s5, s4, 2
	s_or_b32 s4, s4, 3
	s_lshl_b32 s85, s3, 7
	s_and_b32 s82, s6, 52
	s_lshl_b32 s6, s5, 2
	s_lshl_b32 s87, s5, 10
	s_lshl_b32 s5, s4, 2
	s_add_i32 s97, s81, 0
	s_lshl_b32 s3, s3, 14
	s_and_b32 s86, s6, 56
	s_and_b32 s90, s5, 60
	s_lshl_b32 s91, s4, 10
	s_lshl_b32 s96, s8, 3
	s_add_i32 s42, s97, 0x10000
	s_add_i32 s43, s3, 0
	v_sub_f32_e32 v1, v1, v2
	s_bitcmp1_b32 s7, 6
	v_add_f32_e32 v1, 0x3eb60549, v1
	s_cselect_b64 s[6:7], -1, 0
	s_lshl_b32 s2, s2, 15
	s_add_i32 s92, 0, 0x26c40
	v_mbcnt_lo_u32_b32 v2, -1, 0
	s_mov_b32 s45, 0
	v_cmp_eq_u32_e64 s[0:1], 0, v0
	v_cndmask_b32_e64 v1, 1.0, v1, s[6:7]
	s_add_i32 s33, s2, 0
	s_sub_i32 s47, 0, s46
	s_add_i32 s54, s96, 64
	v_mov_b32_e32 v3, 0
	s_movk_i32 s93, 0xff00
	v_cndmask_b32_e64 v243, 0, 1, s[56:57]
	s_mov_b64 s[58:59], 0x80
	s_mov_b64 s[52:53], 0x100
	s_mov_b64 s[48:49], 0x180
	s_movk_i32 s88, 0x80
	s_movk_i32 s89, 0xfee0
	s_mov_b32 s94, 0x3b800000
	s_mov_b32 s84, 0x800000
	v_mov_b32_e32 v245, s92
	v_mov_b32_e32 v246, 0xff
	v_mov_b32_e32 v247, 0xdf
	v_mov_b32_e32 v248, 0xf149f2ca
	v_mbcnt_hi_u32_b32 v249, -1, v2
	v_mov_b32_e32 v244, 0x3727c5ac
	s_mov_b32 s3, 0
	s_mov_b32 s32, 0x20800
	v_lshrrev_b32_e32 v4, 4, v242
	v_and_b32_e32 v5, 15, v242
	v_xor_b32_e32 v5, v5, v4
	v_lshlrev_b32_e32 v5, 4, v5
	v_lshl_add_u32 v4, v4, 12, v5
	v_xor_b32_e32 v5, 64, v4
	v_add_u32_e32 v5, 0x4000, v5
	v_add_u32_e32 v6, 0x8000, v4
	v_add_u32_e32 v7, 0x8000, v5
	v_bfe_u32 v8, v242, 2, 3
	v_and_b32_e32 v9, 3, v242
	v_lshlrev_b32_e32 v9, 4, v9
	v_lshl_add_u32 v8, v8, 12, v9
	v_and_b32_e32 v9, 32, v242
	v_lshl_add_u32 v8, v9, 1, v8
	v_add_u32_e32 v9, 0x80, v8
	v_add_u32_e32 v10, 0x100, v8
	v_add_u32_e32 v11, 0x180, v8
	v_lshl_add_u32 v12, v242, 5, s32
	ds_write_b128 v12, v[4:7]
	ds_write_b128 v12, v[8:11] offset:16
	s_waitcnt lgkmcnt(0)
	s_branch .LBB0_2731

.LBB0_2776:
	v_lshl_add_u32 v8, v242, 5, s32
	ds_read_b128 v[12:15], v8 offset:16
	ds_read_b128 v[8:11], v8
	v_sub_f32_e32 v4, v162, v251
	v_exp_f32_e32 v194, v4
	v_sub_f32_e32 v4, v146, v251
	v_exp_f32_e32 v178, v4
	v_sub_f32_e32 v4, v163, v251
	v_exp_f32_e32 v195, v4
	v_sub_f32_e32 v4, v147, v251
	v_exp_f32_e32 v179, v4
	v_sub_f32_e32 v4, v164, v251
	v_exp_f32_e32 v196, v4
	v_sub_f32_e32 v4, v148, v251
	v_exp_f32_e32 v180, v4
	v_add_f32_e32 v4, v194, v178
	v_add_f32_e32 v181, 0, v4
	v_add_f32_e32 v197, v195, v179
	v_pk_add_f32 v[4:5], v[196:197], v[180:181]
	v_sub_f32_e32 v6, v177, v251
	v_pk_add_f32 v[182:183], v[4:5], v[4:5] op_sel_hi:[0,1]
	v_sub_f32_e32 v4, v165, v251
	v_exp_f32_e32 v197, v4
	v_sub_f32_e32 v4, v149, v251
	v_exp_f32_e32 v181, v4
	v_sub_f32_e32 v4, v166, v251
	v_exp_f32_e32 v198, v4
	v_sub_f32_e32 v4, v150, v251
	v_exp_f32_e32 v182, v4
	v_add_f32_e32 v199, v197, v181
	v_pk_add_f32 v[4:5], v[198:199], v[182:183]
	s_nop 0
	v_pk_add_f32 v[184:185], v[4:5], v[4:5] op_sel_hi:[0,1]
	v_sub_f32_e32 v4, v167, v251
	v_exp_f32_e32 v199, v4
	v_sub_f32_e32 v4, v151, v251
	v_exp_f32_e32 v183, v4
	v_sub_f32_e32 v4, v168, v251
	v_exp_f32_e32 v200, v4
	v_sub_f32_e32 v4, v152, v251
	v_exp_f32_e32 v184, v4
	v_add_f32_e32 v201, v199, v183
	v_pk_add_f32 v[4:5], v[200:201], v[184:185]
	s_nop 0
	v_pk_add_f32 v[186:187], v[4:5], v[4:5] op_sel_hi:[0,1]
	v_sub_f32_e32 v4, v169, v251
	v_exp_f32_e32 v201, v4
	v_sub_f32_e32 v4, v153, v251
	v_exp_f32_e32 v185, v4
	v_sub_f32_e32 v4, v170, v251
	v_exp_f32_e32 v202, v4
	v_sub_f32_e32 v4, v154, v251
	v_exp_f32_e32 v186, v4
	v_add_f32_e32 v203, v201, v185
	v_pk_add_f32 v[4:5], v[202:203], v[186:187]
	s_nop 0
	v_pk_add_f32 v[188:189], v[4:5], v[4:5] op_sel_hi:[0,1]
	v_sub_f32_e32 v4, v171, v251
	v_exp_f32_e32 v203, v4
	v_sub_f32_e32 v4, v155, v251
	v_exp_f32_e32 v187, v4
	v_sub_f32_e32 v4, v172, v251
	v_exp_f32_e32 v204, v4
	v_sub_f32_e32 v4, v156, v251
	v_exp_f32_e32 v188, v4
	v_add_f32_e32 v205, v203, v187
	v_pk_add_f32 v[4:5], v[204:205], v[188:189]
	s_nop 0
	v_pk_add_f32 v[190:191], v[4:5], v[4:5] op_sel_hi:[0,1]
	v_sub_f32_e32 v4, v173, v251
	v_exp_f32_e32 v205, v4
	v_sub_f32_e32 v4, v157, v251
	v_exp_f32_e32 v189, v4
	v_sub_f32_e32 v4, v174, v251
	v_exp_f32_e32 v206, v4
	v_sub_f32_e32 v4, v158, v251
	v_exp_f32_e32 v190, v4
	v_add_f32_e32 v207, v205, v189
	v_pk_add_f32 v[4:5], v[206:207], v[190:191]
	s_nop 0
	v_pk_add_f32 v[192:193], v[4:5], v[4:5] op_sel_hi:[0,1]
	v_sub_f32_e32 v4, v175, v251
	v_exp_f32_e32 v207, v4
	v_sub_f32_e32 v4, v159, v251
	v_exp_f32_e32 v191, v4
	v_sub_f32_e32 v4, v176, v251
	v_exp_f32_e32 v208, v4
	v_sub_f32_e32 v4, v160, v251
	v_exp_f32_e32 v192, v4
	v_add_f32_e32 v209, v207, v191
	v_pk_add_f32 v[4:5], v[208:209], v[192:193]
	v_exp_f32_e32 v209, v6
	v_add_f32_e32 v7, v4, v5
	v_sub_f32_e32 v4, v161, v251
	s_cbranch_execnz .LBB0_2774
.LBB0_2777:
	v_lshl_add_u32 v8, v242, 5, s32
	ds_read_b128 v[12:15], v8 offset:16
	ds_read_b128 v[8:11], v8
	v_sub_f32_e32 v4, v2, v251
	v_fmamk_f32 v2, v162, 0x3e0293ee, v4
	v_exp_f32_e32 v194, v2
	v_fmamk_f32 v2, v146, 0x3e0293ee, v4
	v_exp_f32_e32 v178, v2
	v_fmamk_f32 v2, v163, 0x3e0293ee, v4
	v_exp_f32_e32 v195, v2
	v_fmamk_f32 v2, v147, 0x3e0293ee, v4
	v_exp_f32_e32 v179, v2
	v_fmamk_f32 v2, v164, 0x3e0293ee, v4
	v_exp_f32_e32 v196, v2
	v_fmamk_f32 v2, v148, 0x3e0293ee, v4
	v_exp_f32_e32 v180, v2
	v_add_f32_e32 v2, v194, v178
	v_add_f32_e32 v181, 0, v2
	v_add_f32_e32 v197, v195, v179
	v_fmamk_f32 v2, v165, 0x3e0293ee, v4
	v_pk_add_f32 v[6:7], v[196:197], v[180:181]
	v_exp_f32_e32 v197, v2
	v_fmamk_f32 v2, v149, 0x3e0293ee, v4
	v_exp_f32_e32 v181, v2
	v_fmamk_f32 v2, v166, 0x3e0293ee, v4
	v_pk_add_f32 v[182:183], v[6:7], v[6:7] op_sel_hi:[0,1]
	v_exp_f32_e32 v198, v2
	v_fmamk_f32 v2, v150, 0x3e0293ee, v4
	v_exp_f32_e32 v182, v2
	v_add_f32_e32 v199, v197, v181
	v_fmamk_f32 v2, v167, 0x3e0293ee, v4
	v_pk_add_f32 v[6:7], v[198:199], v[182:183]
	v_exp_f32_e32 v199, v2
	v_fmamk_f32 v2, v151, 0x3e0293ee, v4
	v_exp_f32_e32 v183, v2
	v_fmamk_f32 v2, v168, 0x3e0293ee, v4
	v_pk_add_f32 v[184:185], v[6:7], v[6:7] op_sel_hi:[0,1]
	v_exp_f32_e32 v200, v2
	v_fmamk_f32 v2, v152, 0x3e0293ee, v4
	v_exp_f32_e32 v184, v2
	v_add_f32_e32 v201, v199, v183
	v_fmamk_f32 v2, v169, 0x3e0293ee, v4
	v_pk_add_f32 v[6:7], v[200:201], v[184:185]
	v_exp_f32_e32 v201, v2
	v_fmamk_f32 v2, v153, 0x3e0293ee, v4
	v_exp_f32_e32 v185, v2
	v_fmamk_f32 v2, v170, 0x3e0293ee, v4
	v_pk_add_f32 v[186:187], v[6:7], v[6:7] op_sel_hi:[0,1]
	v_exp_f32_e32 v202, v2
	v_fmamk_f32 v2, v154, 0x3e0293ee, v4
	v_exp_f32_e32 v186, v2
	v_add_f32_e32 v203, v201, v185
	v_fmamk_f32 v2, v171, 0x3e0293ee, v4
	v_pk_add_f32 v[6:7], v[202:203], v[186:187]
	v_exp_f32_e32 v203, v2
	v_fmamk_f32 v2, v155, 0x3e0293ee, v4
	v_exp_f32_e32 v187, v2
	v_fmamk_f32 v2, v172, 0x3e0293ee, v4
	v_pk_add_f32 v[188:189], v[6:7], v[6:7] op_sel_hi:[0,1]
	v_exp_f32_e32 v204, v2
	v_fmamk_f32 v2, v156, 0x3e0293ee, v4
	v_exp_f32_e32 v188, v2
	v_add_f32_e32 v205, v203, v187
	v_fmamk_f32 v2, v173, 0x3e0293ee, v4
	v_pk_add_f32 v[6:7], v[204:205], v[188:189]
	v_exp_f32_e32 v205, v2
	v_fmamk_f32 v2, v157, 0x3e0293ee, v4
	v_exp_f32_e32 v189, v2
	v_fmamk_f32 v2, v174, 0x3e0293ee, v4
	v_pk_add_f32 v[190:191], v[6:7], v[6:7] op_sel_hi:[0,1]
	v_exp_f32_e32 v206, v2
	v_fmamk_f32 v2, v158, 0x3e0293ee, v4
	v_exp_f32_e32 v190, v2
	v_add_f32_e32 v207, v205, v189
	v_fmamk_f32 v2, v175, 0x3e0293ee, v4
	v_pk_add_f32 v[6:7], v[206:207], v[190:191]
	v_exp_f32_e32 v207, v2
	v_fmamk_f32 v2, v159, 0x3e0293ee, v4
	v_exp_f32_e32 v191, v2
	v_fmamk_f32 v2, v176, 0x3e0293ee, v4
	v_pk_add_f32 v[192:193], v[6:7], v[6:7] op_sel_hi:[0,1]
	v_exp_f32_e32 v208, v2
	v_fmamk_f32 v2, v160, 0x3e0293ee, v4
	v_exp_f32_e32 v192, v2
	v_add_f32_e32 v209, v207, v191
	v_fmamk_f32 v2, v177, 0x3e0293ee, v4
	v_fmac_f32_e32 v4, 0x3e0293ee, v161
	v_pk_add_f32 v[6:7], v[208:209], v[192:193]
	v_exp_f32_e32 v209, v2
	v_add_f32_e32 v7, v6, v7
	s_add_i32 s19, s19, 1
	s_cmp_ge_i32 s19, s16
	s_cbranch_scc1 .LBB0_2759
.LBB0_2778:
	s_add_i32 s10, s80, s20
	s_add_i32 s10, s10, 64
	s_lshl_b32 s10, s10, 12
	s_add_u32 s98, s2, s10
	s_addc_u32 s99, s3, 0
	s_add_i32 s8, s21, 0x8000
	s_and_b32 s8, s8, 0x8000
	s_add_i32 s9, s8, 0
	s_waitcnt lgkmcnt(0)
	s_add_i32 m0, s9, s81
	s_add_i32 s10, s54, s20
	global_load_lds_dwordx4 v8, s[98:99]
	s_add_i32 m0, s9, s83
	s_lshl_b32 s10, s10, 12
	global_load_lds_dwordx4 v9, s[98:99]
	s_add_i32 m0, s9, s87
	s_add_i32 s8, s42, s8
	global_load_lds_dwordx4 v10, s[98:99]
	s_add_i32 m0, s9, s91
	s_nop 0
	global_load_lds_dwordx4 v11, s[98:99]
	s_add_u32 s98, s4, s10
	s_addc_u32 s99, s5, 0
	s_mov_b32 m0, s8
	s_nop 0
	global_load_lds_dwordx4 v12, s[98:99]
	s_add_i32 m0, s8, 0x400
	s_nop 0
	global_load_lds_dwordx4 v13, s[98:99]
	s_add_i32 m0, s8, 0x800
	s_nop 0
	global_load_lds_dwordx4 v14, s[98:99]
	s_add_i32 m0, s8, 0xc00
	s_nop 0
	global_load_lds_dwordx4 v15, s[98:99]
	s_branch .LBB0_2759
